# second mixer's deferred weight-conversion filler items now run in a queue pass right after the layer-1 S5 scan body (idle CUs), removed from the later scan/attention phase
# speedup vs baseline: 1.0220x; 1.0060x over previous
_Z4mega6Paramsii:
	v_and_b32_e32 v181, 0x3ff, v0
	s_mov_b32 s100, 0
	v_writelane_b32 v251, s2, 0
	s_add_u32 s2, s0, 0x278
	s_addc_u32 s3, s1, 0
	v_writelane_b32 v251, s2, 1
	s_nop 1
	v_writelane_b32 v251, s3, 2
	v_cmp_eq_u32_e64 s[2:3], 0, v181
	s_mov_b64 s[4:5], exec
	s_nop 0
	v_writelane_b32 v251, s2, 3
	s_nop 1
	v_writelane_b32 v251, s3, 4
	s_and_b64 s[2:3], s[4:5], s[2:3]
	s_mov_b64 exec, s[2:3]
	v_mov_b32_e32 v2, 0
	v_mov_b32_e32 v3, v2
	v_mov_b32_e32 v4, v2
	v_mov_b32_e32 v5, v2
	ds_write_b128 v2, v[2:5]
	s_or_b64 exec, exec, s[4:5]
	s_load_dwordx2 s[2:3], s[0:1], 0x278
	s_load_dwordx2 s[8:9], s[0:1], 0x1d0
	s_waitcnt lgkmcnt(0)
	s_barrier
	v_writelane_b32 v251, s2, 5
	s_nop 1
	v_writelane_b32 v251, s3, 6
	s_getreg_b32 s2, hwreg(HW_REG_XCC_ID, 0, 4)
	s_and_b32 s20, s2, 15
	s_mov_b64 s[6:7], exec
	v_readlane_b32 s2, v251, 3
	v_readlane_b32 s3, v251, 4
	s_and_b64 s[2:3], s[6:7], s[2:3]
	s_mov_b64 exec, s[2:3]
	s_cbranch_execz .LBB0_5
	s_mov_b64 s[2:3], exec
	v_mbcnt_lo_u32_b32 v1, s2, 0
	v_mbcnt_hi_u32_b32 v1, s3, v1
	v_cmp_eq_u32_e32 vcc, 0, v1
	s_and_b64 s[4:5], exec, vcc
	s_mov_b64 exec, s[4:5]
	s_cbranch_execz .LBB0_5
	s_lshl_b32 s4, s20, 8
	s_bcnt1_i32_b64 s2, s[2:3]
	v_mov_b32_e32 v1, s4
	v_mov_b32_e32 v2, s2
	global_atomic_add v1, v2, s[8:9] offset:1024

.LBB0_116:
	s_andn2_b64 vcc, exec, s[2:3]
	s_cbranch_vccnz .LBB0_298
	s_and_b32 s2, s0, 7
	s_cmp_lg_u32 s2, 0
	s_cselect_b64 s[20:21], -1, 0
	s_lshl_b32 s88, s2, 1
	s_cmp_eq_u32 s2, 0
	s_movk_i32 s2, 0x4d8
	s_cselect_b32 s34, s2, 0x400
	s_movk_i32 s2, 0x18c0
	s_cselect_b32 s87, s2, 0x1260
	s_movk_i32 s2, 0xfb28
	s_cselect_b32 s86, s2, 0xfffffc00
	s_cmp_eq_u32 s100, 0
	s_cselect_b32 s101, 0x400, s87
	s_cmp_eq_u32 s88, 2
	s_cselect_b32 s87, s101, s87
	s_lshl_b64 s[2:3], s[0:1], 2
	v_readlane_b32 s4, v253, 11
	v_and_b32_e32 v99, 15, v203
	v_readlane_b32 s5, v253, 12
	s_add_u32 s46, s4, s2
	s_waitcnt vmcnt(5)
	v_lshlrev_b32_e32 v5, 4, v99
	s_addc_u32 s47, s5, s3
	s_lshl_b32 s101, s100, 6
	s_add_u32 s46, s46, s101
	s_addc_u32 s47, s47, 0
	s_waitcnt vmcnt(4)
	v_add_u32_e32 v9, v202, v5
	s_add_i32 s2, 32, 0x100
	v_and_b32_e32 v133, 31, v203
	v_add_u32_e32 v105, s2, v9
	v_add_u32_e32 v107, s2, v5
	v_lshlrev_b32_e32 v2, 2, v134
	s_add_i32 s2, 32, 0x1000
	v_bfe_u32 v3, v203, 5, 1
	s_waitcnt vmcnt(3)
	v_mul_u32_u24_e32 v10, 0x48, v133
	v_add3_u32 v109, v202, v2, s2
	v_lshrrev_b32_e32 v7, 3, v134
	v_lshlrev_b32_e32 v8, 4, v3
	v_lshlrev_b32_e32 v10, 1, v10
	v_lshrrev_b32_e32 v204, 2, v134
	s_movk_i32 s2, 0xffef
	v_or_b32_e32 v6, 32, v7
	v_lshlrev_b32_e32 v11, 4, v134
	v_add3_u32 v180, v135, v8, v10
	v_mul_u32_u24_e32 v8, 0x48, v7
	v_lshrrev_b32_e32 v13, 6, v134
	v_lshlrev_b32_e32 v10, 2, v203
	s_waitcnt vmcnt(1)
	v_bitop3_b32 v18, v204, s2, 15 bitop3:0x6c
	s_movk_i32 s2, 0xffdf
	v_lshlrev_b32_e32 v98, 3, v3
	v_lshlrev_b32_e32 v4, 8, v6
	v_lshlrev_b32_e32 v100, 7, v6
	v_and_b32_e32 v6, 0x70, v11
	v_lshlrev_b32_e32 v8, 1, v8
	v_lshlrev_b32_e32 v104, 2, v3
	v_bfe_u32 v3, v203, 4, 2
	v_lshlrev_b32_e32 v15, 12, v13
	v_and_b32_e32 v110, 12, v10
	v_bitop3_b32 v20, v204, s2, 15 bitop3:0x6c
	v_and_b32_e32 v23, 0xc0, v10
	v_mov_b32_e32 v10, 0x22000
	s_movk_i32 s2, 0x1100
	v_add3_u32 v182, v135, v6, v8
	v_lshl_or_b32 v184, v13, 2, v3
	v_add_u32_e32 v8, v135, v15
	v_lshrrev_b32_e32 v185, 4, v134
	v_mul_i32_i24_e32 v21, 0xfffff010, v13
	v_lshlrev_b32_e32 v22, 2, v3
	v_lshlrev_b32_e32 v3, 8, v99
	v_mad_u32_u24 v10, v7, s2, v10
	s_movk_i32 s2, 0x100
	v_lshlrev_b32_e32 v0, 8, v7
	v_lshlrev_b32_e32 v102, 7, v7
	v_xor_b32_e32 v14, 0xffffffef, v185
	v_add3_u32 v218, v8, v21, v22
	v_add3_u32 v219, v8, v3, v23
	v_mul_u32_u24_e32 v8, 0x1100, v7
	v_add_u32_e32 v7, 32, v15
	v_cmp_gt_u32_e64 s[40:41], s2, v203
	v_cmp_eq_u32_e64 s[42:43], 1, v201
	v_add_u32_e32 v210, 0x100, v14
	v_add_u32_e32 v223, 0x1000, v14
	v_add3_u32 v230, v7, v3, v23
	s_xor_b64 s[44:45], s[40:41], s[42:43]
	v_mov_b32_e32 v3, 0x4000
	v_and_b32_e32 v14, 48, v11
	v_and_b32_e32 v111, 0xc0, v203
	v_and_b32_e32 v106, 63, v203
	v_add_u32_e32 v212, 0x100, v18
	v_add_u32_e32 v224, 0x1000, v18
	v_add3_u32 v229, v7, v21, v22
	v_cndmask_b32_e64 v18, 0, v3, s[44:45]
	v_mul_u32_u24_e32 v3, 0x104, v14
	v_and_b32_e32 v7, 0xfc, v134
	s_mov_b32 s96, s78
	v_add3_u32 v233, v135, v3, v7
	v_lshlrev_b32_e32 v3, 2, v111
	v_lshlrev_b32_e32 v11, 2, v106
	v_readlane_b32 s48, v251, 14
	v_readlane_b32 s4, v252, 48
	v_readlane_b32 s64, v253, 49
	v_lshlrev_b32_e32 v12, 6, v204
	v_lshlrev_b32_e32 v17, 2, v110
	v_add3_u32 v236, v135, v3, v11
	v_mov_b32_e32 v7, v1
	v_readlane_b32 s58, v251, 24
	v_readlane_b32 s59, v251, 25
	v_readlane_b32 s60, v251, 26
	v_readlane_b32 s61, v251, 27
	v_readlane_b32 s62, v251, 28
	v_readlane_b32 s63, v251, 29
	v_readlane_b32 s5, v252, 49
	v_mov_b32_e32 v3, v1
	v_readlane_b32 s78, v253, 63
	v_readlane_b32 s79, v254, 0
	v_add3_u32 v208, v135, v12, v17
	v_add3_u32 v222, 32, v12, v17
	v_and_b32_e32 v12, 60, v2
	v_add_u32_e32 v234, v135, v2
	v_lshl_add_u64 v[112:113], s[58:59], 0, v[6:7]
	v_lshl_add_u64 v[136:137], s[62:63], 0, v[6:7]
	v_lshl_add_u64 v[138:139], s[60:61], 0, v[6:7]
	v_lshl_add_u64 v[140:141], s[4:5], 0, v[6:7]
	v_lshl_add_u64 v[142:143], s[78:79], 0, v[2:3]
	v_and_b32_e32 v2, 7, v203
	v_bfe_u32 v6, v203, 3, 5
	v_lshlrev_b32_e32 v144, 4, v2
	v_lshlrev_b32_e32 v2, 7, v6
	v_xor_b32_e32 v19, 0xffffffdf, v185
	v_lshl_add_u64 v[146:147], s[58:59], 0, v[2:3]
	v_lshl_add_u64 v[150:151], s[60:61], 0, v[2:3]
	v_lshlrev_b32_e32 v2, 1, v8
	v_add_u32_e32 v214, 0x100, v19
	v_add_u32_e32 v225, 0x1000, v19
	v_lshl_add_u32 v19, v12, 2, v135
	s_movk_i32 s2, 0x300
	v_lshlrev_b32_e32 v6, 9, v6
	v_readlane_b32 s3, v253, 7
	v_lshl_add_u64 v[152:153], s[4:5], 0, v[2:3]
	v_or_b32_e32 v2, v15, v11
	v_mad_u32_u24 v235, v185, s2, v19
	v_lshl_add_u64 v[148:149], s[62:63], 0, v[6:7]
	v_add_u32_e32 v6, v202, v15
	v_add_u32_e32 v244, s3, v2
	s_movk_i32 s2, 0xf010
	v_or_b32_e32 v2, v2, v18
	v_add3_u32 v240, v6, v11, s3
	v_mad_i32_i24 v3, v13, s2, v15
	v_add_u32_e32 v246, s3, v2
	v_cmp_ne_u32_e64 s[2:3], 1, v201
	v_readlane_b32 s6, v252, 50
	v_readlane_b32 s7, v252, 51
	v_writelane_b32 v255, s2, 4
	v_readlane_b32 s8, v252, 52
	v_readlane_b32 s9, v252, 53
	v_writelane_b32 v255, s3, 5
	s_and_b64 s[2:3], s[42:43], s[44:45]
	v_writelane_b32 v255, s2, 8
	v_readlane_b32 s10, v252, 54
	v_readlane_b32 s11, v252, 55
	v_readlane_b32 s12, v252, 56
	v_readlane_b32 s13, v252, 57
	v_readlane_b32 s14, v252, 58
	v_readlane_b32 s15, v252, 59
	v_readlane_b32 s16, v252, 60
	v_readlane_b32 s17, v252, 61
	v_readlane_b32 s18, v252, 62
	v_readlane_b32 s19, v252, 63
	v_add3_u32 v6, v6, v21, v22
	v_readlane_b32 s6, v253, 8
	v_readlane_b32 s7, v253, 9
	v_readlane_b32 s8, v253, 10
	v_or_b32_e32 v3, v3, v22
	v_bfe_u32 v2, v203, 4, 4
	v_writelane_b32 v255, s3, 9
	s_movk_i32 s2, 0xc0
	v_bfe_u32 v205, v134, 2, 4
	v_lshlrev_b32_e32 v16, 8, v185
	v_add_u32_e32 v241, s6, v6
	v_add_u32_e32 v242, s7, v6
	v_add_u32_e32 v243, s8, v9
	v_add_u32_e32 v245, s6, v3
	v_add_u32_e32 v247, s7, v3
	v_add_u32_e32 v248, s8, v5
	v_mul_hi_u32_u24_e32 v3, 0x240000, v2
	v_mul_u32_u24_e32 v2, 0x240000, v2
	v_readlane_b32 s4, v254, 25
	v_cmp_gt_u32_e64 s[2:3], s2, v134
	v_add_u32_e32 v206, v135, v16
	v_add_u32_e32 v216, 0x100, v20
	v_lshlrev_b32_e32 v24, 6, v205
	v_add_u32_e32 v226, 0x1000, v20
	v_add_u32_e32 v228, 32, v5
	v_mul_u32_u24_e32 v20, 0x104, v185
	v_readlane_b32 s49, v251, 15
	v_readlane_b32 s52, v251, 18
	v_readlane_b32 s53, v251, 19
	v_readlane_b32 s72, v253, 57
	v_readlane_b32 s73, v253, 58
	v_readlane_b32 s74, v253, 59
	v_readlane_b32 s75, v253, 60
	v_or_b32_e32 v2, v2, v5
	v_readlane_b32 s5, v254, 26
	v_writelane_b32 v255, s2, 6
	s_mov_b32 s89, s29
	v_mov_b32_e32 v101, v1
	v_mov_b32_e32 v103, v1
	v_add_u32_e32 v183, 0x1200, v182
	v_lshlrev_b32_e32 v108, 2, v99
	v_add_u32_e32 v207, v206, v5
	v_or_b32_e32 v209, 16, v185
	v_or_b32_e32 v211, 16, v205
	v_or_b32_e32 v213, 32, v185
	v_or_b32_e32 v215, 32, v205
	v_add_u32_e32 v217, v135, v5
	v_add3_u32 v220, v135, v24, v17
	v_add3_u32 v221, 32, v16, v5
	v_or_b32_e32 v227, -16, v203
	v_add_u32_e32 v231, v230, v18
	v_or_b32_e32 v232, 0xff0, v203
	v_add_u32_e32 v237, v228, v16
	v_add3_u32 v238, 32, v24, v17
	s_mov_b64 s[74:75], s[46:47]
	s_mov_b64 s[72:73], s[20:21]
	v_or_b32_e32 v239, 32, v204
	v_mov_b32_e32 v145, v1
	v_or_b32_e32 v249, 0x300, v134
	v_lshl_add_u64 v[154:155], s[4:5], 0, v[2:3]
	v_lshlrev_b32_e32 v156, 1, v4
	v_lshlrev_b32_e32 v158, 1, v0
	v_lshlrev_b32_e32 v160, 1, v10
	v_lshlrev_b32_e32 v162, 1, v8
	v_lshlrev_b32_e32 v164, 2, v12
	v_add_u32_e32 v250, v19, v20
	v_lshlrev_b32_e32 v166, 1, v14
	v_cmp_eq_u32_e64 s[46:47], 0, v203
	v_cmp_gt_u32_e64 s[48:49], 64, v134
	s_xor_b64 s[52:53], s[44:45], -1
	v_writelane_b32 v255, s3, 7
	v_readlane_b32 s50, v251, 16
	v_readlane_b32 s51, v251, 17
	v_readlane_b32 s54, v251, 20
	v_readlane_b32 s55, v251, 21
	v_readlane_b32 s56, v251, 22
	v_readlane_b32 s57, v251, 23
	v_readlane_b32 s65, v253, 50
	v_readlane_b32 s66, v253, 51
	v_readlane_b32 s67, v253, 52
	v_readlane_b32 s68, v253, 53
	v_readlane_b32 s69, v253, 54
	v_readlane_b32 s70, v253, 55
	v_readlane_b32 s71, v253, 56
	v_readlane_b32 s76, v253, 61
	v_readlane_b32 s77, v253, 62
	v_readlane_b32 s6, v254, 27
	v_readlane_b32 s7, v254, 28
	v_readlane_b32 s8, v254, 29
	v_readlane_b32 s9, v254, 30
	v_readlane_b32 s10, v254, 31
	v_readlane_b32 s11, v254, 32
	v_readlane_b32 s12, v254, 33
	v_readlane_b32 s13, v254, 34
	v_readlane_b32 s14, v254, 35
	v_readlane_b32 s15, v254, 36
	v_readlane_b32 s16, v254, 37
	v_readlane_b32 s17, v254, 38
	v_readlane_b32 s18, v254, 39
	v_readlane_b32 s19, v254, 40
	s_branch .LBB0_121

.LBB0_124:
	s_or_b64 exec, exec, s[20:21]
	s_waitcnt vmcnt(0)
	v_readfirstlane_b32 s20, v2
	s_lshl_b32 s101, s100, 10
	s_add_i32 s20, s20, s101
	s_nop 1
	v_add_u32_e32 v0, s20, v0
	ds_write_b32 v1, v0 offset:16

.LBB0_664:
	v_readlane_b32 s52, v254, 59
	v_readlane_b32 s53, v254, 60
	s_cmp_eq_u32 s100, 1
	s_cbranch_scc1 .Lvf_end
	s_cmp_eq_u32 s52, 19
	s_cbranch_scc0 .Lvf_norm
	s_mov_b32 s100, 1
	s_mov_b32 s52, 32
	s_branch .Lvf_norm
.Lvf_end:
	s_mov_b32 s100, 0
	s_mov_b32 s52, 19
.Lvf_norm:
	s_add_i32 s52, s52, 1
	s_cmp_ge_i32 s52, s53
	s_cselect_b64 s[0:1], -1, 0
	s_cmp_lt_i32 s52, s53
	v_readlane_b32 s4, v251, 56
	s_cselect_b64 s[2:3], -1, 0
	v_readlane_b32 s5, v251, 57
	s_and_b64 s[2:3], s[4:5], s[2:3]
	s_cmp_eq_u32 s100, 1
	s_cselect_b64 s[2:3], 0, s[2:3]
	v_readlane_b32 s54, v254, 43
	v_readlane_b32 s56, v254, 45
	v_readlane_b32 s58, v254, 47
	v_readlane_b32 s60, v254, 49
	v_readlane_b32 s6, v251, 10
	s_andn2_b64 vcc, exec, s[2:3]
	v_readlane_b32 s55, v254, 44
	v_readlane_b32 s57, v254, 46
	v_readlane_b32 s59, v254, 48
	v_readlane_b32 s61, v254, 50
	v_readlane_b32 s62, v254, 51
	v_readlane_b32 s64, v254, 53
	v_readlane_b32 s66, v254, 55
	v_readlane_b32 s7, v251, 11
	v_readlane_b32 s63, v254, 52
	v_readlane_b32 s65, v254, 54
	v_readlane_b32 s67, v254, 56
	s_cbranch_vccnz .LBB0_9
	v_readlane_b32 s2, v251, 58
	v_readlane_b32 s3, v251, 59
	s_andn2_b64 vcc, exec, s[2:3]
	s_cbranch_vccnz .LBB0_677
	v_readlane_b32 s4, v253, 13
	v_readlane_b32 s5, v253, 14
	s_waitcnt vmcnt(63) expcnt(7) lgkmcnt(15)
	s_barrier
	s_and_saveexec_b64 s[2:3], s[4:5]
	s_cbranch_execz .LBB0_676
	v_readlane_b32 s20, v251, 1
	v_readlane_b32 s21, v251, 2
	buffer_wbl2 sc1
	s_waitcnt vmcnt(0)
	s_load_dwordx2 s[20:21], s[20:21], 0x58
	s_mov_b64 s[40:41], exec
	v_mbcnt_lo_u32_b32 v2, s40, 0
	v_mbcnt_hi_u32_b32 v2, s41, v2
	v_cmp_eq_u32_e32 vcc, 0, v2
	s_waitcnt lgkmcnt(0)
	global_load_dword v0, v1, s[20:21] offset:40
	s_and_saveexec_b64 s[42:43], vcc
	s_cbranch_execz .LBB0_669
	s_bcnt1_i32_b64 s24, s[40:41]
	v_mov_b32_e32 v3, s24
	global_atomic_add v3, v1, v3, s[20:21] offset:32 sc0

	.amdhsa_kernel _Z4mega6Paramsii
		.amdhsa_group_segment_fixed_size 32
		.amdhsa_private_segment_fixed_size 0
		.amdhsa_kernarg_size 888
		.amdhsa_user_sgpr_count 2
		.amdhsa_user_sgpr_dispatch_ptr 0
		.amdhsa_user_sgpr_queue_ptr 0
		.amdhsa_user_sgpr_kernarg_segment_ptr 1
		.amdhsa_user_sgpr_dispatch_id 0
		.amdhsa_user_sgpr_kernarg_preload_length 0
		.amdhsa_user_sgpr_kernarg_preload_offset 0
		.amdhsa_user_sgpr_private_segment_size 0
		.amdhsa_uses_dynamic_stack 0
		.amdhsa_enable_private_segment 0
		.amdhsa_system_sgpr_workgroup_id_x 1
		.amdhsa_system_sgpr_workgroup_id_y 0
		.amdhsa_system_sgpr_workgroup_id_z 0
		.amdhsa_system_sgpr_workgroup_info 0
		.amdhsa_system_vgpr_workitem_id 2
		.amdhsa_next_free_vgpr 256
		.amdhsa_next_free_sgpr 102
		.amdhsa_accum_offset 256
		.amdhsa_reserve_vcc 1
		.amdhsa_float_round_mode_32 0
		.amdhsa_float_round_mode_16_64 0
		.amdhsa_float_denorm_mode_32 3
		.amdhsa_float_denorm_mode_16_64 3
		.amdhsa_dx10_clamp 1
		.amdhsa_ieee_mode 1
		.amdhsa_fp16_overflow 0
		.amdhsa_tg_split 0
		.amdhsa_exception_fp_ieee_invalid_op 0
		.amdhsa_exception_fp_denorm_src 0
		.amdhsa_exception_fp_ieee_div_zero 0
		.amdhsa_exception_fp_ieee_overflow 0
		.amdhsa_exception_fp_ieee_underflow 0
		.amdhsa_exception_fp_ieee_inexact 0
		.amdhsa_exception_int_div_zero 0
	.end_amdhsa_kernel

amdhsa.kernels:
  - .agpr_count:     0
    .args:
      - .offset:         0
        .size:           624
        .value_kind:     by_value
      - .offset:         624
        .size:           4
        .value_kind:     by_value
      - .offset:         628
        .size:           4
        .value_kind:     by_value
      - .offset:         632
        .size:           4
        .value_kind:     hidden_block_count_x
      - .offset:         636
        .size:           4
        .value_kind:     hidden_block_count_y
      - .offset:         640
        .size:           4
        .value_kind:     hidden_block_count_z
      - .offset:         644
        .size:           2
        .value_kind:     hidden_group_size_x
      - .offset:         646
        .size:           2
        .value_kind:     hidden_group_size_y
      - .offset:         648
        .size:           2
        .value_kind:     hidden_group_size_z
      - .offset:         650
        .size:           2
        .value_kind:     hidden_remainder_x
      - .offset:         652
        .size:           2
        .value_kind:     hidden_remainder_y
      - .offset:         654
        .size:           2
        .value_kind:     hidden_remainder_z
      - .offset:         672
        .size:           8
        .value_kind:     hidden_global_offset_x
      - .offset:         680
        .size:           8
        .value_kind:     hidden_global_offset_y
      - .offset:         688
        .size:           8
        .value_kind:     hidden_global_offset_z
      - .offset:         696
        .size:           2
        .value_kind:     hidden_grid_dims
      - .offset:         720
        .size:           8
        .value_kind:     hidden_multigrid_sync_arg
      - .offset:         752
        .size:           4
        .value_kind:     hidden_dynamic_lds_size
    .group_segment_fixed_size: 32
    .kernarg_segment_align: 8
    .kernarg_segment_size: 888
    .language:       OpenCL C
    .language_version:
      - 2
      - 0
    .max_flat_workgroup_size: 512
    .name:           _Z4mega6Paramsii
    .private_segment_fixed_size: 0
    .sgpr_count:     108
    .sgpr_spill_count: 302
    .symbol:         _Z4mega6Paramsii.kd
    .uniform_work_group_size: 1
    .uses_dynamic_stack: false
    .vgpr_count:     256
    .vgpr_spill_count: 0
    .wavefront_size: 64
